# s6 layer-0 xb 16-B stores write-through (sc1)
# baseline (speedup 1.0000x reference)
.LBB0_365:
	s_andn2_b64 vcc, exec, s[2:3]
	v_lshl_add_u64 v[152:153], v[194:195], 1, s[80:81]
	v_lshl_add_u64 v[152:153], v[152:153], 0, v[228:229]
	s_cbranch_vccnz .LBB0_367
	v_cvt_pk_bf16_f32 v32, v32, v33
	v_cvt_pk_bf16_f32 v33, v34, v35
	v_mov_b32_e32 v34, v193
	v_mov_b32_e32 v35, v193
	v_mov_b32_e32 v224, v32
	v_mov_b32_e32 v225, v33
	v_pk_mul_f32 v[32:33], v[162:163], v[158:159]
	v_pk_mul_f32 v[34:35], v[34:35], v[154:155]
	v_pk_fma_f32 v[32:33], v[16:17], v[32:33], v[20:21]
	v_pk_fma_f32 v[34:35], v[18:19], v[34:35], v[22:23]
	global_store_dwordx4 v[156:157], v[32:35], off offset:64 sc1
	s_nop 1
	v_cvt_pk_bf16_f32 v32, v32, v33
	v_cvt_pk_bf16_f32 v33, v34, v35
	v_mov_b32_e32 v226, v32
	v_mov_b32_e32 v227, v33
	s_nop 1
	v_permlane16_swap_b32_e32 v224, v226
	v_permlane16_swap_b32_e32 v225, v227
	s_nop 1
	global_store_dwordx4 v[152:153], v[224:227], off sc1

.LBB0_369:
	s_andn2_b64 vcc, exec, s[2:3]
	s_cbranch_vccnz .LBB0_371
	v_cvt_pk_bf16_f32 v32, v32, v33
	v_cvt_pk_bf16_f32 v33, v34, v35
	v_mov_b32_e32 v192, v193
	v_mov_b32_e32 v224, v32
	v_mov_b32_e32 v225, v33
	v_pk_mul_f32 v[32:33], v[162:163], v[144:145]
	v_pk_mul_f32 v[34:35], v[192:193], v[146:147]
	v_pk_fma_f32 v[32:33], v[0:1], v[32:33], v[4:5]
	v_pk_fma_f32 v[34:35], v[2:3], v[34:35], v[6:7]
	global_store_dwordx4 v[156:157], v[32:35], off offset:576 sc1
	s_nop 1
	v_cvt_pk_bf16_f32 v32, v32, v33
	v_cvt_pk_bf16_f32 v33, v34, v35
	v_mov_b32_e32 v226, v32
	v_mov_b32_e32 v227, v33
	s_nop 1
	v_permlane16_swap_b32_e32 v224, v226
	v_permlane16_swap_b32_e32 v225, v227
	s_nop 1
	global_store_dwordx4 v[152:153], v[224:227], off offset:256 sc1

.LBB0_373:
	s_andn2_b64 vcc, exec, s[2:3]
	v_lshl_add_u64 v[136:137], v[148:149], 1, s[80:81]
	v_lshl_add_u64 v[136:137], v[136:137], 0, v[228:229]
	s_cbranch_vccnz .LBB0_375
	v_cvt_pk_bf16_f32 v32, v32, v33
	v_cvt_pk_bf16_f32 v33, v34, v35
	v_mov_b32_e32 v34, v145
	v_mov_b32_e32 v35, v145
	v_mov_b32_e32 v224, v32
	v_mov_b32_e32 v225, v33
	v_pk_mul_f32 v[32:33], v[146:147], v[142:143]
	v_pk_mul_f32 v[34:35], v[34:35], v[138:139]
	v_pk_fma_f32 v[32:33], v[16:17], v[32:33], v[20:21]
	v_pk_fma_f32 v[34:35], v[18:19], v[34:35], v[22:23]
	global_store_dwordx4 v[140:141], v[32:35], off offset:64 sc1
	s_nop 1
	v_cvt_pk_bf16_f32 v32, v32, v33
	v_cvt_pk_bf16_f32 v33, v34, v35
	v_mov_b32_e32 v226, v32
	v_mov_b32_e32 v227, v33
	s_nop 1
	v_permlane16_swap_b32_e32 v224, v226
	v_permlane16_swap_b32_e32 v225, v227
	s_nop 1
	global_store_dwordx4 v[136:137], v[224:227], off sc1

.LBB0_377:
	s_andn2_b64 vcc, exec, s[2:3]
	s_cbranch_vccnz .LBB0_379
	v_cvt_pk_bf16_f32 v32, v32, v33
	v_cvt_pk_bf16_f32 v33, v34, v35
	v_mov_b32_e32 v144, v145
	v_mov_b32_e32 v224, v32
	v_mov_b32_e32 v225, v33
	v_pk_mul_f32 v[32:33], v[146:147], v[128:129]
	v_pk_mul_f32 v[34:35], v[144:145], v[130:131]
	v_pk_fma_f32 v[32:33], v[0:1], v[32:33], v[4:5]
	v_pk_fma_f32 v[34:35], v[2:3], v[34:35], v[6:7]
	global_store_dwordx4 v[140:141], v[32:35], off offset:576 sc1
	s_nop 1
	v_cvt_pk_bf16_f32 v32, v32, v33
	v_cvt_pk_bf16_f32 v33, v34, v35
	v_mov_b32_e32 v226, v32
	v_mov_b32_e32 v227, v33
	s_nop 1
	v_permlane16_swap_b32_e32 v224, v226
	v_permlane16_swap_b32_e32 v225, v227
	s_nop 1
	global_store_dwordx4 v[136:137], v[224:227], off offset:256 sc1

.LBB0_381:
	s_andn2_b64 vcc, exec, s[2:3]
	v_lshl_add_u64 v[120:121], v[132:133], 1, s[80:81]
	v_lshl_add_u64 v[120:121], v[120:121], 0, v[228:229]
	s_cbranch_vccnz .LBB0_383
	v_cvt_pk_bf16_f32 v32, v32, v33
	v_cvt_pk_bf16_f32 v33, v34, v35
	v_mov_b32_e32 v34, v129
	v_mov_b32_e32 v35, v129
	v_mov_b32_e32 v224, v32
	v_mov_b32_e32 v225, v33
	v_pk_mul_f32 v[32:33], v[130:131], v[126:127]
	v_pk_mul_f32 v[34:35], v[34:35], v[122:123]
	v_pk_fma_f32 v[32:33], v[16:17], v[32:33], v[20:21]
	v_pk_fma_f32 v[34:35], v[18:19], v[34:35], v[22:23]
	global_store_dwordx4 v[124:125], v[32:35], off offset:64 sc1
	s_nop 1
	v_cvt_pk_bf16_f32 v32, v32, v33
	v_cvt_pk_bf16_f32 v33, v34, v35
	v_mov_b32_e32 v226, v32
	v_mov_b32_e32 v227, v33
	s_nop 1
	v_permlane16_swap_b32_e32 v224, v226
	v_permlane16_swap_b32_e32 v225, v227
	s_nop 1
	global_store_dwordx4 v[120:121], v[224:227], off sc1

.LBB0_385:
	s_andn2_b64 vcc, exec, s[2:3]
	s_cbranch_vccnz .LBB0_387
	v_cvt_pk_bf16_f32 v32, v32, v33
	v_cvt_pk_bf16_f32 v33, v34, v35
	v_mov_b32_e32 v128, v129
	v_mov_b32_e32 v224, v32
	v_mov_b32_e32 v225, v33
	v_pk_mul_f32 v[32:33], v[130:131], v[112:113]
	v_pk_mul_f32 v[34:35], v[128:129], v[114:115]
	v_pk_fma_f32 v[32:33], v[0:1], v[32:33], v[4:5]
	v_pk_fma_f32 v[34:35], v[2:3], v[34:35], v[6:7]
	global_store_dwordx4 v[124:125], v[32:35], off offset:576 sc1
	s_nop 1
	v_cvt_pk_bf16_f32 v32, v32, v33
	v_cvt_pk_bf16_f32 v33, v34, v35
	v_mov_b32_e32 v226, v32
	v_mov_b32_e32 v227, v33
	s_nop 1
	v_permlane16_swap_b32_e32 v224, v226
	v_permlane16_swap_b32_e32 v225, v227
	s_nop 1
	global_store_dwordx4 v[120:121], v[224:227], off offset:256 sc1

.LBB0_389:
	s_andn2_b64 vcc, exec, s[2:3]
	v_lshl_add_u64 v[104:105], v[116:117], 1, s[80:81]
	v_lshl_add_u64 v[104:105], v[104:105], 0, v[228:229]
	s_cbranch_vccnz .LBB0_391
	v_cvt_pk_bf16_f32 v32, v32, v33
	v_cvt_pk_bf16_f32 v33, v34, v35
	v_mov_b32_e32 v34, v113
	v_mov_b32_e32 v35, v113
	v_mov_b32_e32 v224, v32
	v_mov_b32_e32 v225, v33
	v_pk_mul_f32 v[32:33], v[114:115], v[110:111]
	v_pk_mul_f32 v[34:35], v[34:35], v[106:107]
	v_pk_fma_f32 v[32:33], v[16:17], v[32:33], v[20:21]
	v_pk_fma_f32 v[34:35], v[18:19], v[34:35], v[22:23]
	global_store_dwordx4 v[108:109], v[32:35], off offset:64 sc1
	s_nop 1
	v_cvt_pk_bf16_f32 v32, v32, v33
	v_cvt_pk_bf16_f32 v33, v34, v35
	v_mov_b32_e32 v226, v32
	v_mov_b32_e32 v227, v33
	s_nop 1
	v_permlane16_swap_b32_e32 v224, v226
	v_permlane16_swap_b32_e32 v225, v227
	s_nop 1
	global_store_dwordx4 v[104:105], v[224:227], off sc1

.LBB0_393:
	s_andn2_b64 vcc, exec, s[2:3]
	s_cbranch_vccnz .LBB0_395
	v_cvt_pk_bf16_f32 v32, v32, v33
	v_cvt_pk_bf16_f32 v33, v34, v35
	v_mov_b32_e32 v112, v113
	v_mov_b32_e32 v224, v32
	v_mov_b32_e32 v225, v33
	v_pk_mul_f32 v[32:33], v[114:115], v[96:97]
	v_pk_mul_f32 v[34:35], v[112:113], v[98:99]
	v_pk_fma_f32 v[32:33], v[0:1], v[32:33], v[4:5]
	v_pk_fma_f32 v[34:35], v[2:3], v[34:35], v[6:7]
	global_store_dwordx4 v[108:109], v[32:35], off offset:576 sc1
	s_nop 1
	v_cvt_pk_bf16_f32 v32, v32, v33
	v_cvt_pk_bf16_f32 v33, v34, v35
	v_mov_b32_e32 v226, v32
	v_mov_b32_e32 v227, v33
	s_nop 1
	v_permlane16_swap_b32_e32 v224, v226
	v_permlane16_swap_b32_e32 v225, v227
	s_nop 1
	global_store_dwordx4 v[104:105], v[224:227], off offset:256 sc1

.LBB0_397:
	s_andn2_b64 vcc, exec, s[2:3]
	v_lshl_add_u64 v[88:89], v[100:101], 1, s[80:81]
	v_lshl_add_u64 v[88:89], v[88:89], 0, v[228:229]
	s_cbranch_vccnz .LBB0_399
	v_cvt_pk_bf16_f32 v32, v32, v33
	v_cvt_pk_bf16_f32 v33, v34, v35
	v_mov_b32_e32 v34, v97
	v_mov_b32_e32 v35, v97
	v_mov_b32_e32 v224, v32
	v_mov_b32_e32 v225, v33
	v_pk_mul_f32 v[32:33], v[98:99], v[94:95]
	v_pk_mul_f32 v[34:35], v[34:35], v[90:91]
	v_pk_fma_f32 v[32:33], v[16:17], v[32:33], v[20:21]
	v_pk_fma_f32 v[34:35], v[18:19], v[34:35], v[22:23]
	global_store_dwordx4 v[92:93], v[32:35], off offset:64 sc1
	s_nop 1
	v_cvt_pk_bf16_f32 v32, v32, v33
	v_cvt_pk_bf16_f32 v33, v34, v35
	v_mov_b32_e32 v226, v32
	v_mov_b32_e32 v227, v33
	s_nop 1
	v_permlane16_swap_b32_e32 v224, v226
	v_permlane16_swap_b32_e32 v225, v227
	s_nop 1
	global_store_dwordx4 v[88:89], v[224:227], off sc1

.LBB0_401:
	s_andn2_b64 vcc, exec, s[2:3]
	s_cbranch_vccnz .LBB0_403
	v_cvt_pk_bf16_f32 v32, v32, v33
	v_cvt_pk_bf16_f32 v33, v34, v35
	v_mov_b32_e32 v96, v97
	v_mov_b32_e32 v224, v32
	v_mov_b32_e32 v225, v33
	v_pk_mul_f32 v[32:33], v[98:99], v[80:81]
	v_pk_mul_f32 v[34:35], v[96:97], v[82:83]
	v_pk_fma_f32 v[32:33], v[0:1], v[32:33], v[4:5]
	v_pk_fma_f32 v[34:35], v[2:3], v[34:35], v[6:7]
	global_store_dwordx4 v[92:93], v[32:35], off offset:576 sc1
	s_nop 1
	v_cvt_pk_bf16_f32 v32, v32, v33
	v_cvt_pk_bf16_f32 v33, v34, v35
	v_mov_b32_e32 v226, v32
	v_mov_b32_e32 v227, v33
	s_nop 1
	v_permlane16_swap_b32_e32 v224, v226
	v_permlane16_swap_b32_e32 v225, v227
	s_nop 1
	global_store_dwordx4 v[88:89], v[224:227], off offset:256 sc1

.LBB0_405:
	s_andn2_b64 vcc, exec, s[2:3]
	v_lshl_add_u64 v[72:73], v[84:85], 1, s[80:81]
	v_lshl_add_u64 v[72:73], v[72:73], 0, v[228:229]
	s_cbranch_vccnz .LBB0_407
	v_cvt_pk_bf16_f32 v32, v32, v33
	v_cvt_pk_bf16_f32 v33, v34, v35
	v_mov_b32_e32 v34, v81
	v_mov_b32_e32 v35, v81
	v_mov_b32_e32 v224, v32
	v_mov_b32_e32 v225, v33
	v_pk_mul_f32 v[32:33], v[82:83], v[78:79]
	v_pk_mul_f32 v[34:35], v[34:35], v[74:75]
	v_pk_fma_f32 v[32:33], v[16:17], v[32:33], v[20:21]
	v_pk_fma_f32 v[34:35], v[18:19], v[34:35], v[22:23]
	global_store_dwordx4 v[76:77], v[32:35], off offset:64 sc1
	s_nop 1
	v_cvt_pk_bf16_f32 v32, v32, v33
	v_cvt_pk_bf16_f32 v33, v34, v35
	v_mov_b32_e32 v226, v32
	v_mov_b32_e32 v227, v33
	s_nop 1
	v_permlane16_swap_b32_e32 v224, v226
	v_permlane16_swap_b32_e32 v225, v227
	s_nop 1
	global_store_dwordx4 v[72:73], v[224:227], off sc1

.LBB0_409:
	s_andn2_b64 vcc, exec, s[2:3]
	s_cbranch_vccnz .LBB0_411
	v_cvt_pk_bf16_f32 v32, v32, v33
	v_cvt_pk_bf16_f32 v33, v34, v35
	v_mov_b32_e32 v80, v81
	v_mov_b32_e32 v224, v32
	v_mov_b32_e32 v225, v33
	v_pk_mul_f32 v[32:33], v[82:83], v[64:65]
	v_pk_mul_f32 v[34:35], v[80:81], v[66:67]
	v_pk_fma_f32 v[32:33], v[0:1], v[32:33], v[4:5]
	v_pk_fma_f32 v[34:35], v[2:3], v[34:35], v[6:7]
	global_store_dwordx4 v[76:77], v[32:35], off offset:576 sc1
	s_nop 1
	v_cvt_pk_bf16_f32 v32, v32, v33
	v_cvt_pk_bf16_f32 v33, v34, v35
	v_mov_b32_e32 v226, v32
	v_mov_b32_e32 v227, v33
	s_nop 1
	v_permlane16_swap_b32_e32 v224, v226
	v_permlane16_swap_b32_e32 v225, v227
	s_nop 1
	global_store_dwordx4 v[72:73], v[224:227], off offset:256 sc1

.LBB0_413:
	s_andn2_b64 vcc, exec, s[2:3]
	v_lshl_add_u64 v[56:57], v[68:69], 1, s[80:81]
	v_lshl_add_u64 v[56:57], v[56:57], 0, v[228:229]
	s_cbranch_vccnz .LBB0_415
	v_cvt_pk_bf16_f32 v32, v32, v33
	v_cvt_pk_bf16_f32 v33, v34, v35
	v_mov_b32_e32 v34, v65
	v_mov_b32_e32 v35, v65
	v_mov_b32_e32 v224, v32
	v_mov_b32_e32 v225, v33
	v_pk_mul_f32 v[32:33], v[66:67], v[62:63]
	v_pk_mul_f32 v[34:35], v[34:35], v[58:59]
	v_pk_fma_f32 v[32:33], v[16:17], v[32:33], v[20:21]
	v_pk_fma_f32 v[34:35], v[18:19], v[34:35], v[22:23]
	global_store_dwordx4 v[60:61], v[32:35], off offset:64 sc1
	s_nop 1
	v_cvt_pk_bf16_f32 v32, v32, v33
	v_cvt_pk_bf16_f32 v33, v34, v35
	v_mov_b32_e32 v226, v32
	v_mov_b32_e32 v227, v33
	s_nop 1
	v_permlane16_swap_b32_e32 v224, v226
	v_permlane16_swap_b32_e32 v225, v227
	s_nop 1
	global_store_dwordx4 v[56:57], v[224:227], off sc1

.LBB0_417:
	s_andn2_b64 vcc, exec, s[2:3]
	s_cbranch_vccnz .LBB0_419
	v_cvt_pk_bf16_f32 v32, v32, v33
	v_cvt_pk_bf16_f32 v33, v34, v35
	v_mov_b32_e32 v64, v65
	v_mov_b32_e32 v224, v32
	v_mov_b32_e32 v225, v33
	v_pk_mul_f32 v[32:33], v[66:67], v[48:49]
	v_pk_mul_f32 v[34:35], v[64:65], v[50:51]
	v_pk_fma_f32 v[32:33], v[0:1], v[32:33], v[4:5]
	v_pk_fma_f32 v[34:35], v[2:3], v[34:35], v[6:7]
	global_store_dwordx4 v[60:61], v[32:35], off offset:576 sc1
	s_nop 1
	v_cvt_pk_bf16_f32 v32, v32, v33
	v_cvt_pk_bf16_f32 v33, v34, v35
	v_mov_b32_e32 v226, v32
	v_mov_b32_e32 v227, v33
	s_nop 1
	v_permlane16_swap_b32_e32 v224, v226
	v_permlane16_swap_b32_e32 v225, v227
	s_nop 1
	global_store_dwordx4 v[56:57], v[224:227], off offset:256 sc1

.LBB0_421:
	s_andn2_b64 vcc, exec, s[2:3]
	v_lshl_add_u64 v[30:31], v[48:49], 1, s[80:81]
	v_lshl_add_u64 v[30:31], v[30:31], 0, v[228:229]
	s_cbranch_vccnz .LBB0_423
	v_cvt_pk_bf16_f32 v24, v24, v25
	v_cvt_pk_bf16_f32 v25, v26, v27
	v_mov_b32_e32 v26, v33
	v_mov_b32_e32 v27, v33
	v_mov_b32_e32 v224, v24
	v_mov_b32_e32 v225, v25
	v_pk_mul_f32 v[24:25], v[34:35], v[40:41]
	v_pk_mul_f32 v[26:27], v[26:27], v[42:43]
	v_pk_fma_f32 v[16:17], v[16:17], v[24:25], v[20:21]
	v_pk_fma_f32 v[18:19], v[18:19], v[26:27], v[22:23]
	global_store_dwordx4 v[28:29], v[16:19], off offset:64 sc1
	s_nop 1
	v_cvt_pk_bf16_f32 v16, v16, v17
	v_cvt_pk_bf16_f32 v17, v18, v19
	v_mov_b32_e32 v226, v16
	v_mov_b32_e32 v227, v17
	s_nop 1
	v_permlane16_swap_b32_e32 v224, v226
	v_permlane16_swap_b32_e32 v225, v227
	s_nop 1
	global_store_dwordx4 v[30:31], v[224:227], off sc1

.LBB0_425:
	s_andn2_b64 vcc, exec, s[2:3]
	s_cbranch_vccnz .LBB0_427
	v_cvt_pk_bf16_f32 v8, v8, v9
	v_cvt_pk_bf16_f32 v9, v10, v11
	v_mov_b32_e32 v32, v33
	v_mov_b32_e32 v224, v8
	v_mov_b32_e32 v225, v9
	v_pk_mul_f32 v[8:9], v[34:35], v[14:15]
	v_pk_mul_f32 v[10:11], v[32:33], v[12:13]
	v_pk_fma_f32 v[0:1], v[0:1], v[8:9], v[4:5]
	v_pk_fma_f32 v[2:3], v[2:3], v[10:11], v[6:7]
	global_store_dwordx4 v[28:29], v[0:3], off offset:576 sc1
	s_nop 1
	v_cvt_pk_bf16_f32 v0, v0, v1
	v_cvt_pk_bf16_f32 v1, v2, v3
	v_mov_b32_e32 v226, v0
	v_mov_b32_e32 v227, v1
	s_nop 1
	v_permlane16_swap_b32_e32 v224, v226
	v_permlane16_swap_b32_e32 v225, v227
	s_nop 1
	global_store_dwordx4 v[30:31], v[224:227], off offset:256 sc1
